# baseline (speedup 1.0000x reference)
.LBB0_648:
	v_ashrrev_i64 v[8:9], 7, v[0:1]
	v_bfe_u32 v10, v0, 4, 3
	v_lshlrev_b64 v[4:5], 5, v[8:9]
	v_lshl_add_u64 v[4:5], s[10:11], 0, v[4:5]
	v_lshlrev_b32_e32 v128, 2, v10
	v_lshl_add_u64 v[4:5], v[4:5], 0, v[128:129]
	v_add_co_u32_e32 v6, vcc, 0x40000, v4
	global_load_dword v11, v[4:5], off
	s_nop 0
	v_addc_co_u32_e32 v7, vcc, 0, v5, vcc
	global_load_dword v6, v[6:7], off
	v_add_co_u32_e32 v4, vcc, 0x80000, v4
	v_lshlrev_b64 v[8:9], 10, v[8:9]
	s_nop 0
	v_addc_co_u32_e32 v5, vcc, 0, v5, vcc
	global_load_dword v4, v[4:5], off
	v_lshl_or_b32 v28, v10, 7, v8
	v_and_b32_e32 v29, 0x78, v2
	v_or_b32_e32 v28, v28, v29
	v_mov_b32_e32 v29, v9
	v_lshlrev_b64 v[28:29], 1, v[28:29]
	v_lshl_add_u64 v[30:31], s[90:91], 0, v[28:29]
	global_load_dwordx4 v[32:35], v[30:31], off nt
	v_lshl_add_u64 v[30:31], s[12:13], 0, v[28:29]
	global_load_dwordx4 v[36:39], v[30:31], off nt
	v_lshl_add_u64 v[30:31], s[94:95], 0, v[28:29]
	global_load_dwordx4 v[40:43], v[30:31], off nt
	v_lshl_add_u64 v[0:1], v[0:1], 0, s[8:9]
	s_waitcnt vmcnt(3)
	v_max3_f32 v5, v11, v6, v4
	v_sub_f32_e32 v7, v11, v5
	v_sub_f32_e32 v6, v6, v5
	v_exp_f32_e32 v7, v7
	v_exp_f32_e32 v6, v6
	v_sub_f32_e32 v4, v4, v5
	v_exp_f32_e32 v4, v4
	v_add_f32_e32 v5, v7, v6
	v_add_f32_e32 v5, v4, v5
	v_div_scale_f32 v11, s[0:1], v5, v5, 1.0
	v_rcp_f32_e32 v12, v11
	s_mov_b64 s[0:1], 0xfffff
	v_fma_f32 v13, -v11, v12, 1.0
	v_fmac_f32_e32 v12, v13, v12
	v_div_scale_f32 v13, vcc, 1.0, v5, 1.0
	v_mul_f32_e32 v14, v13, v12
	v_fma_f32 v15, -v11, v14, v13
	v_fmac_f32_e32 v14, v15, v12
	v_fma_f32 v11, -v11, v14, v13
	v_div_fmas_f32 v11, v11, v12, v14
	v_div_fixup_f32 v20, v11, v5, 1.0
	v_lshl_or_b32 v5, v10, 7, v8
	v_and_b32_e32 v8, 0x78, v2
	v_or_b32_e32 v8, v5, v8
	v_lshlrev_b64 v[22:23], 1, v[8:9]
	v_lshl_add_u64 v[8:9], s[90:91], 0, v[22:23]
	v_lshl_add_u64 v[12:13], s[12:13], 0, v[22:23]
	v_lshl_add_u64 v[16:17], s[94:95], 0, v[22:23]
	v_mul_f32_e32 v4, v4, v20
	v_pk_mul_f32 v[20:21], v[6:7], v[20:21] op_sel_hi:[1,0]
	v_cmp_lt_i64_e32 vcc, s[0:1], v[0:1]
	v_lshl_add_u64 v[2:3], v[2:3], 0, s[28:29]
	s_or_b64 s[6:7], vcc, s[6:7]
	s_waitcnt vmcnt(0)
	v_mov_b32_e32 v8, v32
	v_mov_b32_e32 v9, v33
	v_mov_b32_e32 v10, v34
	v_mov_b32_e32 v11, v35
	v_mov_b32_e32 v12, v36
	v_mov_b32_e32 v13, v37
	v_mov_b32_e32 v14, v38
	v_mov_b32_e32 v15, v39
	v_mov_b32_e32 v16, v40
	v_mov_b32_e32 v17, v41
	v_mov_b32_e32 v18, v42
	v_mov_b32_e32 v19, v43
	v_lshlrev_b32_e32 v24, 16, v8
	v_and_b32_e32 v7, 0xffff0000, v8
	s_waitcnt vmcnt(1)
	v_and_b32_e32 v25, 0xffff0000, v12
	v_lshlrev_b32_e32 v6, 16, v12
	v_pk_mul_f32 v[24:25], v[20:21], v[24:25] op_sel:[1,0] op_sel_hi:[0,1]
	v_pk_fma_f32 v[6:7], v[20:21], v[6:7], v[24:25]
	v_and_b32_e32 v25, 0xffff0000, v9
	v_lshlrev_b32_e32 v8, 16, v9
	v_and_b32_e32 v9, 0xffff0000, v13
	v_lshlrev_b32_e32 v24, 16, v13
	v_pk_mul_f32 v[8:9], v[20:21], v[8:9] op_sel:[1,0] op_sel_hi:[0,1]
	s_waitcnt vmcnt(0)
	v_lshlrev_b32_e32 v26, 16, v16
	v_and_b32_e32 v27, 0xffff0000, v16
	v_lshlrev_b32_e32 v12, 16, v17
	v_and_b32_e32 v13, 0xffff0000, v17
	v_pk_fma_f32 v[8:9], v[20:21], v[24:25], v[8:9]
	v_pk_fma_f32 v[6:7], v[4:5], v[26:27], v[6:7] op_sel_hi:[0,1,1]
	v_pk_fma_f32 v[8:9], v[4:5], v[12:13], v[8:9] op_sel_hi:[0,1,1]
	v_lshlrev_b32_e32 v12, 16, v10
	v_and_b32_e32 v13, 0xffff0000, v14
	v_cvt_pk_bf16_f32 v6, v6, v7
	v_cvt_pk_bf16_f32 v7, v8, v9
	v_lshlrev_b32_e32 v8, 16, v14
	v_and_b32_e32 v9, 0xffff0000, v10
	v_pk_mul_f32 v[12:13], v[20:21], v[12:13] op_sel:[1,0] op_sel_hi:[0,1]
	v_pk_fma_f32 v[8:9], v[20:21], v[8:9], v[12:13]
	v_and_b32_e32 v13, 0xffff0000, v11
	v_lshlrev_b32_e32 v10, 16, v11
	v_and_b32_e32 v11, 0xffff0000, v15
	v_lshlrev_b32_e32 v12, 16, v15
	v_pk_mul_f32 v[10:11], v[20:21], v[10:11] op_sel:[1,0] op_sel_hi:[0,1]
	v_lshlrev_b32_e32 v16, 16, v18
	v_and_b32_e32 v17, 0xffff0000, v18
	v_pk_fma_f32 v[10:11], v[20:21], v[12:13], v[10:11]
	v_lshlrev_b32_e32 v12, 16, v19
	v_and_b32_e32 v13, 0xffff0000, v19
	v_pk_fma_f32 v[8:9], v[4:5], v[16:17], v[8:9] op_sel_hi:[0,1,1]
	v_pk_fma_f32 v[4:5], v[4:5], v[12:13], v[10:11] op_sel_hi:[0,1,1]
	v_cvt_pk_bf16_f32 v8, v8, v9
	v_cvt_pk_bf16_f32 v9, v4, v5
	v_lshl_add_u64 v[4:5], s[14:15], 0, v[22:23]
	global_store_dwordx4 v[4:5], v[6:9], off
	s_andn2_b64 exec, exec, s[6:7]
	s_cbranch_execnz .LBB0_648
